# P0-end seam: the grid-sync word is loaded under the drain of the wave's stores, in front of the seam's entry barrier, so the release check in front of the census post costs no extra round trip; on top
# speedup vs baseline: 1.0002x; 1.0002x over previous
; __device__ __forceinline__ int lane_id_asm() { int l; asm volatile("v_mbcnt_lo_u32_b32 %0, -1, 0\n\tv_mbcnt_hi_u32_b32 %0, -1, %0" : "=v"(l)); return l; }
; __device__ __forceinline__ void xcd_barrier(const XcdBarrier& b, const int wid) {
;     asm volatile("s_waitcnt vmcnt(0)" ::: "memory");
;     __syncthreads();
;     if (wid == 0 && lane_id_asm() == 0) {
.LBB0_207:
	v_cndmask_b32_e64 v0, 0, 1, s[0:1]
	v_cmp_ne_u32_e64 s[2:3], 1, v0
	s_andn2_b64 vcc, exec, s[0:1]
	s_nop 0
	v_writelane_b32 v254, s2, 13
	s_nop 1
	v_writelane_b32 v254, s3, 14
	s_cbranch_vccnz .LBB0_259
	s_add_u32 s2, s72, 0x110
	s_addc_u32 s3, s73, 0
	s_load_dwordx2 s[2:3], s[2:3], 0x58
	v_mov_b32_e32 v18, 0
	s_waitcnt lgkmcnt(0)
	global_load_dword v19, v18, s[2:3] offset:32 sc1
	s_waitcnt vmcnt(0)
	s_cmp_gt_u32 s79, 63
	s_barrier
	s_cbranch_scc1 .LBB0_258
	v_mbcnt_lo_u32_b32 v0, -1, 0
	v_mbcnt_hi_u32_b32 v0, -1, v0
	s_nop 0
	v_cmp_eq_u32_e32 vcc, 0, v0
	s_and_saveexec_b64 s[0:1], vcc
	s_cbranch_execz .LBB0_257
	v_mov_b32_e32 v2, 0x25730
	ds_read_b32 v1, v2
	v_mov_b32_e32 v0, 0
	s_waitcnt lgkmcnt(0)
	v_and_b32_e32 v2, 0xffff0000, v19
	v_cmp_ne_u32_e32 vcc, v2, v1
	s_cbranch_vccnz .Lcg_out
